# weight-conversion phase: the 4 tiles' loads of an iteration issued before any is consumed; mix-norm: 15 of the 32 per-row gate-weight loads hoisted out of the row loop into spare VGPRs
# speedup vs baseline: 1.1404x; 1.0079x over previous
; #define LAS __attribute__((address_space(3)))
; __device__ __forceinline__ void phase_cvt(const Ctx& c, int l) {
;     ...
;             dsts[u] = dst; ldds[u] = ldd; nz[u] = (src != nullptr);
;             LAS float* tile = (LAS float*)c.lds + u * (64 * 65);
;             if (src) {
;                 const int i = tid >> 4, j4 = tid & 15;
; #pragma unroll
;                 for (int r = 0; r < 2; ++r) { const int k = i + 32 * r; const f32x4 v = *(const f32x4*)(src + (size_t)k * ld + 4 * j4);
;                     tile[k * 65 + 4 * j4 + 0] = v[0]; tile[k * 65 + 4 * j4 + 1] = v[1]; tile[k * 65 + 4 * j4 + 2] = v[2]; tile[k * 65 + 4 * j4 + 3] = v[3]; }
;             }
.LBB0_59:
	v_mov_b32_e32 v7, v31
	s_waitcnt vmcnt(5)
	v_lshl_add_u64 v[16:17], s[4:5], 0, v[6:7]
	v_mul_lo_u32 v7, s19, v0
	v_mul_lo_u32 v14, s18, v3
	v_mad_u64_u32 v[12:13], s[4:5], s18, v0, 0
	v_add3_u32 v13, v13, v14, v7
	v_lshl_add_u64 v[12:13], v[12:13], 2, v[16:17]
	v_mul_lo_u32 v7, s19, v4
	s_waitcnt vmcnt(4)
	v_mul_lo_u32 v20, s18, v5
	v_mad_u64_u32 v[18:19], s[4:5], s18, v4, 0
	global_load_dwordx4 v[200:203], v[12:13], off
	v_add3_u32 v19, v19, v20, v7
	v_lshl_add_u64 v[16:17], v[18:19], 2, v[16:17]
	global_load_dwordx4 v[204:207], v[16:17], off

; __device__ __forceinline__ void phase_cvt(const Ctx& c, int l) {
;     ...
;             if (src) {
;                 const int i = tid >> 4, j4 = tid & 15;
; #pragma unroll
;                 for (int r = 0; r < 2; ++r) { const int k = i + 32 * r; const f32x4 v = *(const f32x4*)(src + (size_t)k * ld + 4 * j4);
;                     tile[k * 65 + 4 * j4 + 0] = v[0]; tile[k * 65 + 4 * j4 + 1] = v[1]; tile[k * 65 + 4 * j4 + 2] = v[2]; tile[k * 65 + 4 * j4 + 3] = v[3]; }
;             }
.LBB0_96:
	v_mov_b32_e32 v7, v31
	s_waitcnt vmcnt(7)
	v_lshl_add_u64 v[16:17], s[4:5], 0, v[6:7]
	v_mul_lo_u32 v7, s25, v0
	v_mul_lo_u32 v14, s24, v3
	v_mad_u64_u32 v[12:13], s[4:5], s24, v0, 0
	v_add3_u32 v13, v13, v14, v7
	v_lshl_add_u64 v[12:13], v[12:13], 2, v[16:17]
	v_mul_lo_u32 v7, s25, v4
	s_waitcnt vmcnt(6)
	v_mul_lo_u32 v20, s24, v5
	v_mad_u64_u32 v[18:19], s[4:5], s24, v4, 0
	global_load_dwordx4 v[208:211], v[12:13], off
	v_add3_u32 v19, v19, v20, v7
	v_lshl_add_u64 v[16:17], v[18:19], 2, v[16:17]
	global_load_dwordx4 v[212:215], v[16:17], off

; __device__ __forceinline__ void phase_cvt(const Ctx& c, int l) {
;     ...
;             if (src) {
;                 const int i = tid >> 4, j4 = tid & 15;
; #pragma unroll
;                 for (int r = 0; r < 2; ++r) { const int k = i + 32 * r; const f32x4 v = *(const f32x4*)(src + (size_t)k * ld + 4 * j4);
;                     tile[k * 65 + 4 * j4 + 0] = v[0]; tile[k * 65 + 4 * j4 + 1] = v[1]; tile[k * 65 + 4 * j4 + 2] = v[2]; tile[k * 65 + 4 * j4 + 3] = v[3]; }
;             }
.LBB0_133:
	v_mov_b32_e32 v7, v31
	s_waitcnt vmcnt(9)
	v_lshl_add_u64 v[16:17], s[4:5], 0, v[6:7]
	v_mul_lo_u32 v7, s31, v0
	v_mul_lo_u32 v14, s30, v3
	v_mad_u64_u32 v[12:13], s[4:5], s30, v0, 0
	v_add3_u32 v13, v13, v14, v7
	v_lshl_add_u64 v[12:13], v[12:13], 2, v[16:17]
	v_mul_lo_u32 v7, s31, v4
	s_waitcnt vmcnt(8)
	v_mul_lo_u32 v20, s30, v5
	v_mad_u64_u32 v[18:19], s[4:5], s30, v4, 0
	global_load_dwordx4 v[216:219], v[12:13], off
	v_add3_u32 v19, v19, v20, v7
	v_lshl_add_u64 v[16:17], v[18:19], 2, v[16:17]
	global_load_dwordx4 v[220:223], v[16:17], off

; __device__ __forceinline__ void phase_cvt(const Ctx& c, int l) {
;     ...
;             if (src) {
;                 const int i = tid >> 4, j4 = tid & 15;
; #pragma unroll
;                 for (int r = 0; r < 2; ++r) { const int k = i + 32 * r; const f32x4 v = *(const f32x4*)(src + (size_t)k * ld + 4 * j4);
;                     tile[k * 65 + 4 * j4 + 0] = v[0]; tile[k * 65 + 4 * j4 + 1] = v[1]; tile[k * 65 + 4 * j4 + 2] = v[2]; tile[k * 65 + 4 * j4 + 3] = v[3]; }
;             }
.LBB0_170:
	v_mov_b32_e32 v7, v31
	s_waitcnt vmcnt(11)
	v_lshl_add_u64 v[16:17], s[4:5], 0, v[6:7]
	v_mul_lo_u32 v7, s39, v0
	v_mul_lo_u32 v14, s38, v3
	v_mad_u64_u32 v[12:13], s[4:5], s38, v0, 0
	v_add3_u32 v13, v13, v14, v7
	v_lshl_add_u64 v[12:13], v[12:13], 2, v[16:17]
	v_mul_lo_u32 v7, s39, v4
	s_waitcnt vmcnt(10)
	v_mul_lo_u32 v20, s38, v5
	v_mad_u64_u32 v[18:19], s[4:5], s38, v4, 0
	global_load_dwordx4 v[224:227], v[12:13], off
	v_add3_u32 v19, v19, v20, v7
	v_lshl_add_u64 v[16:17], v[18:19], 2, v[16:17]
	global_load_dwordx4 v[228:231], v[16:17], off
.LBB0_171:
	s_waitcnt vmcnt(0)
	s_and_b64 vcc, exec, s[16:17]
	s_cbranch_vccz .Lcvt_sk0
	ds_write2_b32 v8, v200, v201 offset1:1
	ds_write2_b32 v8, v202, v203 offset0:2 offset1:3
	ds_write2_b32 v9, v204, v205 offset1:1
	ds_write2_b32 v10, v206, v207 offset1:1
.Lcvt_sk0:
	s_and_b64 vcc, exec, s[22:23]
	s_cbranch_vccz .Lcvt_sk1
	v_add_u32_e32 v7, 0x4100, v8
	v_add_u32_e32 v20, 0x4108, v8
	v_add_u32_e32 v21, 0x6180, v8
	v_add_u32_e32 v22, 0x6188, v8
	ds_write2_b32 v7, v208, v209 offset1:1
	ds_write2_b32 v20, v210, v211 offset1:1
	ds_write2_b32 v21, v212, v213 offset1:1
	ds_write2_b32 v22, v214, v215 offset1:1
.Lcvt_sk1:
	s_and_b64 vcc, exec, s[28:29]
	s_cbranch_vccz .Lcvt_sk2
	v_add_u32_e32 v7, 0x8200, v8
	v_add_u32_e32 v20, 0x8208, v8
	v_add_u32_e32 v21, 0xa280, v8
	v_add_u32_e32 v22, 0xa288, v8
	ds_write2_b32 v7, v216, v217 offset1:1
	ds_write2_b32 v20, v218, v219 offset1:1
	ds_write2_b32 v21, v220, v221 offset1:1
	ds_write2_b32 v22, v222, v223 offset1:1
.Lcvt_sk2:
	s_and_b64 vcc, exec, s[36:37]
	s_cbranch_vccz .Lcvt_sk3
	v_add_u32_e32 v7, 0xc300, v8
	v_add_u32_e32 v20, 0xc308, v8
	v_add_u32_e32 v21, 0xe380, v8
	v_add_u32_e32 v22, 0xe388, v8
	ds_write2_b32 v7, v224, v225 offset1:1
	ds_write2_b32 v20, v226, v227 offset1:1
	ds_write2_b32 v21, v228, v229 offset1:1
	ds_write2_b32 v22, v230, v231 offset1:1

; #define X (outg(c))
; __device__ __forceinline__ void phase_norm(const Ctx& c, const float* xin_p, const float* xin_s, float* X, int grow0, int nrows, const float* gamma, bf16_t* dst, const float* wif, float* gif) {
;     ...
;     f32x4 gm[4];
; #pragma unroll
;     for (int i = 0; i < 4; ++i) gm[i] = *(const f32x4*)(gamma + 256 * i + 4 * lane);
;     for (int r = c.bid * 8 + c.wave; r < nrows; r += c.G * 8) {
;         const int gr = grow0 + r;
;         const float* src = xin_p ? (gr < NPROMPT ? xin_p + (size_t)gr * D : xin_s + (size_t)(gr - NPROMPT) * D) : X + (size_t)gr * D;
;         f32x4 v[4]; float ss = 0.f;
; #pragma unroll
;         for (int i = 0; i < 4; ++i) { v[i] = *(const f32x4*)(src + 256 * i + 4 * lane); ss += v[i][0] * v[i][0] + v[i][1] * v[i][1] + v[i][2] * v[i][2] + v[i][3] * v[i][3]; }
;         if (xin_p && gr >= NPROMPT) {
; #pragma unroll
;             for (int i = 0; i < 4; ++i) *(f32x4*)(X + (size_t)gr * D + 256 * i + 4 * lane) = v[i];
;         }
;         ss = wsum(ss);
;         const float rstd = __builtin_amdgcn_rsqf(ss * (1.0f / D) + 1e-6f);
; #pragma unroll
;         for (int i = 0; i < 4; ++i) {
;             v[i] = v[i] * rstd * gm[i];
;             u32x2 w; w.x = pk2(v[i][0], v[i][1]); w.y = pk2(v[i][2], v[i][3]);
;             *(u32x2*)(dst + (size_t)r * D + 256 * i + 4 * lane) = w;
;         }
;         if (gif) {
;             float a8[8];
; #pragma unroll
;             for (int j = 0; j < 8; ++j) a8[j] = 0.f;
; #pragma unroll
;             for (int i = 0; i < 4; ++i)
; #pragma unroll
;                 for (int e = 0; e < 4; ++e) {
;                     const float* wp = wif + (size_t)(256 * i + 4 * lane + e) * 8; const f32x4 w0 = *(const f32x4*)wp, w1 = *(const f32x4*)(wp + 4);
.LBB0_407:
	s_andn2_b64 vcc, exec, s[2:3]
	s_cbranch_vccnz .LBB0_424
	v_readlane_b32 s2, v254, 40
	v_readlane_b32 s3, v254, 41
	v_readlane_b32 s4, v254, 43
	v_readlane_b32 s3, v254, 42
	v_readlane_b32 s5, v254, 44
	s_add_i32 s0, s84, 0x23e68
	v_writelane_b32 v254, s4, 43
	v_mov_b32_e32 v0, s0
	ds_read2_b32 v[0:1], v0 offset1:1
	v_writelane_b32 v254, s5, 44
	v_writelane_b32 v254, s2, 40
	s_lshl_b32 s8, s78, 3
	s_add_i32 s0, s8, s3
	v_writelane_b32 v254, s3, 41
	v_writelane_b32 v254, s3, 42
	s_waitcnt lgkmcnt(0)
	v_readfirstlane_b32 s3, v1
	v_readlane_b32 s2, v254, 48
	s_cmp_ge_i32 s0, s2
	v_readfirstlane_b32 s2, v0
	s_cbranch_scc1 .LBB0_413
	v_readlane_b32 s4, v254, 23
	v_readlane_b32 s5, v254, 24
	s_lshl_b64 s[4:5], s[4:5], 2
	s_waitcnt vmcnt(5)
	v_lshlrev_b32_e32 v16, 2, v182
	s_add_u32 s2, s2, s4
	v_ashrrev_i32_e32 v17, 31, v16
	s_addc_u32 s3, s3, s5
	v_lshlrev_b64 v[18:19], 2, v[16:17]
	v_lshl_add_u64 v[12:13], s[2:3], 0, v[18:19]
	global_load_dwordx4 v[0:3], v[12:13], off
	global_load_dwordx4 v[4:7], v[12:13], off offset:1024
	global_load_dwordx4 v[8:11], v[12:13], off offset:2048
	s_nop 0
	global_load_dwordx4 v[12:15], v[12:13], off offset:3072
	s_waitcnt vmcnt(8)
	v_and_b32_e32 v20, 64, v164
	v_add_u32_e32 v20, 64, v20
	v_xor_b32_e32 v21, 32, v164
	v_cmp_lt_i32_e32 vcc, v21, v20
	v_readlane_b32 s2, v254, 46
	s_lshl_b32 s9, s2, 14
	v_cndmask_b32_e32 v21, v164, v21, vcc
	v_lshlrev_b32_e32 v30, 2, v21
	v_xor_b32_e32 v21, 16, v164
	v_cmp_lt_i32_e32 vcc, v21, v20
	s_add_u32 s2, s82, 0x4200000
	s_addc_u32 s3, s83, 0
	v_cndmask_b32_e32 v21, v164, v21, vcc
	v_lshlrev_b32_e32 v92, 2, v21
	v_xor_b32_e32 v21, 8, v164
	v_cmp_lt_i32_e32 vcc, v21, v20
	v_readlane_b32 s14, v254, 42
	s_ashr_i32 s4, s8, 31
	v_cndmask_b32_e32 v21, v164, v21, vcc
	v_lshlrev_b32_e32 v93, 2, v21
	v_xor_b32_e32 v21, 4, v164
	v_cmp_lt_i32_e32 vcc, v21, v20
	s_nop 1
	v_cndmask_b32_e32 v21, v164, v21, vcc
	v_lshlrev_b32_e32 v94, 2, v21
	v_xor_b32_e32 v21, 2, v164
	v_cmp_lt_i32_e32 vcc, v21, v20
	s_nop 1
	v_cndmask_b32_e32 v21, v164, v21, vcc
	v_lshlrev_b32_e32 v95, 2, v21
	v_xor_b32_e32 v21, 1, v164
	v_cmp_lt_i32_e32 vcc, v21, v20
	s_nop 1
	v_cndmask_b32_e32 v20, v164, v21, vcc
	v_lshlrev_b32_e32 v96, 2, v20
	v_lshlrev_b64 v[20:21], 5, v[16:17]
	v_lshl_add_u64 v[28:29], s[2:3], 0, v[20:21]
	v_or_b32_e32 v20, 2, v16
	v_ashrrev_i32_e32 v21, 31, v20
	v_lshlrev_b64 v[20:21], 5, v[20:21]
	v_lshl_add_u64 v[60:61], s[2:3], 0, v[20:21]
	s_mov_b64 s[2:3], 0x2000
	v_lshl_add_u64 v[62:63], v[28:29], 0, s[2:3]
	s_mov_b64 s[2:3], 0x2040
	v_lshl_add_u64 v[64:65], v[28:29], 0, s[2:3]
	s_mov_b64 s[2:3], 0x4000
	v_lshl_add_u64 v[66:67], v[28:29], 0, s[2:3]
	s_mov_b64 s[2:3], 0x4040
	v_lshl_add_u64 v[68:69], v[28:29], 0, s[2:3]
	s_mov_b64 s[2:3], 0x6000
	v_lshl_add_u64 v[70:71], v[28:29], 0, s[2:3]
	s_mov_b64 s[2:3], 0x6040
	v_lshl_add_u64 v[72:73], v[28:29], 0, s[2:3]
	v_readlane_b32 s2, v254, 40
	v_readlane_b32 s3, v254, 41
	s_lshl_b32 s2, s2, 3
	s_ashr_i32 s3, s14, 31
	s_add_u32 s10, s14, s8
	s_addc_u32 s11, s3, s4
	s_add_i32 s9, s14, s9
	s_add_i32 s8, s9, s8
	s_ashr_i32 s3, s2, 31
	s_ashr_i32 s9, s8, 31
	s_lshl_b64 s[4:5], s[10:11], 5
	s_lshl_b64 s[6:7], s[2:3], 5
	s_lshl_b64 s[8:9], s[8:9], 12
	v_readlane_b32 s14, v254, 43
	v_readlane_b32 s15, v254, 44
	s_add_u32 s8, s14, s8
	s_addc_u32 s9, s15, s9
	v_lshl_add_u64 v[18:19], s[8:9], 0, v[18:19]
	s_mov_b64 s[8:9], 0xc00
	s_waitcnt vmcnt(4)
	v_lshl_add_u64 v[74:75], v[18:19], 0, s[8:9]
	s_lshl_b64 s[8:9], s[2:3], 12
	s_lshl_b64 s[10:11], s[10:11], 11
	s_add_u32 s10, s10, 0x4208400
	s_addc_u32 s11, s11, 0
	v_cmp_eq_u32_e32 vcc, 0, v182
	v_lshl_add_u64 v[76:77], v[16:17], 1, s[10:11]
	s_lshl_b64 s[10:11], s[2:3], 11
	global_load_dwordx4 v[192:195], v[66:67], off offset:16
	global_load_dwordx4 v[196:199], v[66:67], off offset:32
	global_load_dwordx4 v[200:203], v[66:67], off
	global_load_dwordx4 v[204:207], v[68:69], off offset:48
	global_load_dwordx4 v[208:211], v[68:69], off offset:32
	global_load_dwordx4 v[212:215], v[68:69], off offset:16
	global_load_dwordx4 v[216:219], v[68:69], off
	global_load_dwordx4 v[220:223], v[70:71], off offset:48
	global_load_dwordx4 v[224:227], v[70:71], off offset:16
	global_load_dwordx4 v[228:231], v[70:71], off offset:32
	global_load_dwordx4 v[232:235], v[70:71], off
	global_load_dwordx4 v[236:239], v[72:73], off offset:48
	global_load_dwordx4 v[240:243], v[72:73], off offset:16
	global_load_dwordx4 v[244:247], v[72:73], off offset:32
	global_load_dwordx4 v[248:251], v[72:73], off
	s_branch .LBB0_411

; #define X (outg(c))
; __device__ __forceinline__ void phase_norm(const Ctx& c, const float* xin_p, const float* xin_s, float* X, int grow0, int nrows, const float* gamma, bf16_t* dst, const float* wif, float* gif) {
;     ...
;     for (int r = c.bid * 8 + c.wave; r < nrows; r += c.G * 8) {
;         const int gr = grow0 + r;
;         const float* src = xin_p ? (gr < NPROMPT ? xin_p + (size_t)gr * D : xin_s + (size_t)(gr - NPROMPT) * D) : X + (size_t)gr * D;
;         f32x4 v[4]; float ss = 0.f;
; #pragma unroll
;         for (int i = 0; i < 4; ++i) { v[i] = *(const f32x4*)(src + 256 * i + 4 * lane); ss += v[i][0] * v[i][0] + v[i][1] * v[i][1] + v[i][2] * v[i][2] + v[i][3] * v[i][3]; }
;         if (xin_p && gr >= NPROMPT) {
; #pragma unroll
;             for (int i = 0; i < 4; ++i) *(f32x4*)(X + (size_t)gr * D + 256 * i + 4 * lane) = v[i];
;         }
;         ss = wsum(ss);
;         const float rstd = __builtin_amdgcn_rsqf(ss * (1.0f / D) + 1e-6f);
; #pragma unroll
;         for (int i = 0; i < 4; ++i) {
;             v[i] = v[i] * rstd * gm[i];
;             u32x2 w; w.x = pk2(v[i][0], v[i][1]); w.y = pk2(v[i][2], v[i][3]);
;             *(u32x2*)(dst + (size_t)r * D + 256 * i + 4 * lane) = w;
;         }
;         if (gif) {
;             float a8[8];
; #pragma unroll
;             for (int j = 0; j < 8; ++j) a8[j] = 0.f;
; #pragma unroll
;             for (int i = 0; i < 4; ++i)
; #pragma unroll
;                 for (int e = 0; e < 4; ++e) {
;                     const float* wp = wif + (size_t)(256 * i + 4 * lane + e) * 8; const f32x4 w0 = *(const f32x4*)wp, w1 = *(const f32x4*)(wp + 4);
;                     a8[0] += v[i][e] * w0[0]; a8[1] += v[i][e] * w0[1]; a8[2] += v[i][e] * w0[2]; a8[3] += v[i][e] * w0[3];
;                     a8[4] += v[i][e] * w1[0]; a8[5] += v[i][e] * w1[1]; a8[6] += v[i][e] * w1[2]; a8[7] += v[i][e] * w1[3];
.LBB0_411:
	global_load_dwordx4 v[16:19], v[74:75], off offset:-3072
	global_load_dwordx4 v[24:27], v[74:75], off offset:-2048
	global_load_dwordx4 v[32:35], v[74:75], off offset:-1024
	global_load_dwordx4 v[38:41], v[74:75], off
	s_waitcnt lgkmcnt(6)
	v_lshl_add_u64 v[44:45], s[82:83], 0, v[76:77]
	s_waitcnt vmcnt(3) lgkmcnt(3)
	v_mul_f32_e32 v20, v17, v17
	s_waitcnt vmcnt(2) lgkmcnt(2)
	v_mul_f32_e32 v21, v25, v25
	v_fmac_f32_e32 v20, v16, v16
	v_fmac_f32_e32 v21, v24, v24
	v_fmac_f32_e32 v20, v18, v18
	v_fmac_f32_e32 v21, v26, v26
	v_fmac_f32_e32 v20, v19, v19
	v_fmac_f32_e32 v21, v27, v27
	s_waitcnt vmcnt(1) lgkmcnt(1)
	v_mov_b32_e32 v22, v33
	s_waitcnt vmcnt(0) lgkmcnt(0)
	v_mov_b32_e32 v23, v39
	v_add_f32_e32 v36, v20, v21
	v_mov_b32_e32 v20, v32
	v_mov_b32_e32 v21, v38
	v_pk_mul_f32 v[22:23], v[22:23], v[22:23]
	s_nop 0
	v_pk_fma_f32 v[20:21], v[20:21], v[20:21], v[22:23]
	v_mov_b32_e32 v22, v34
	v_mov_b32_e32 v23, v40
	v_pk_fma_f32 v[20:21], v[22:23], v[22:23], v[20:21]
	v_mov_b32_e32 v22, v35
	v_mov_b32_e32 v23, v41
	v_pk_fma_f32 v[20:21], v[22:23], v[22:23], v[20:21]
	s_nop 0
	v_add_f32_e32 v20, v36, v20
	v_add_f32_e32 v20, v20, v21
	ds_bpermute_b32 v21, v30, v20
	s_waitcnt lgkmcnt(0)
	v_add_f32_e32 v20, v20, v21
	ds_bpermute_b32 v21, v92, v20
	s_waitcnt lgkmcnt(0)
	v_add_f32_e32 v20, v20, v21
	ds_bpermute_b32 v21, v93, v20
	s_waitcnt lgkmcnt(0)
	v_add_f32_e32 v20, v20, v21
	ds_bpermute_b32 v21, v94, v20
	s_waitcnt lgkmcnt(0)
	v_add_f32_e32 v20, v20, v21
	ds_bpermute_b32 v21, v95, v20
	s_waitcnt lgkmcnt(0)
	v_add_f32_e32 v20, v20, v21
	ds_bpermute_b32 v21, v96, v20
	s_waitcnt lgkmcnt(0)
	v_add_f32_e32 v20, v20, v21
	v_fmamk_f32 v20, v20, 0x3a800000, v162
	v_rsq_f32_e32 v42, v20
	s_nop 0
	v_pk_mul_f32 v[16:17], v[16:17], v[42:43] op_sel_hi:[1,0]
	v_pk_mul_f32 v[18:19], v[18:19], v[42:43] op_sel_hi:[1,0]
	v_pk_mul_f32 v[22:23], v[0:1], v[16:17]
	v_pk_mul_f32 v[20:21], v[2:3], v[18:19]
	v_cvt_pk_bf16_f32 v16, v22, v23
	v_cvt_pk_bf16_f32 v17, v20, v21
	global_store_dwordx2 v[44:45], v[16:17], off offset:-1024
	v_pk_mul_f32 v[16:17], v[24:25], v[42:43] op_sel_hi:[1,0]
	v_pk_mul_f32 v[18:19], v[26:27], v[42:43] op_sel_hi:[1,0]
	v_pk_mul_f32 v[26:27], v[4:5], v[16:17]
	v_pk_mul_f32 v[24:25], v[6:7], v[18:19]
	v_cvt_pk_bf16_f32 v16, v26, v27
	v_cvt_pk_bf16_f32 v17, v24, v25
	global_store_dwordx2 v[44:45], v[16:17], off offset:-512
	v_pk_mul_f32 v[16:17], v[32:33], v[42:43] op_sel_hi:[1,0]
	v_pk_mul_f32 v[18:19], v[34:35], v[42:43] op_sel_hi:[1,0]
	v_pk_mul_f32 v[36:37], v[8:9], v[16:17]
	v_pk_mul_f32 v[80:81], v[10:11], v[18:19]
	v_cvt_pk_bf16_f32 v16, v36, v37
	v_cvt_pk_bf16_f32 v17, v80, v81
	global_store_dwordx2 v[44:45], v[16:17], off
	v_pk_mul_f32 v[16:17], v[38:39], v[42:43] op_sel_hi:[1,0]
	v_pk_mul_f32 v[18:19], v[40:41], v[42:43] op_sel_hi:[1,0]
	v_pk_mul_f32 v[82:83], v[12:13], v[16:17]
	v_pk_mul_f32 v[78:79], v[14:15], v[18:19]
	v_cvt_pk_bf16_f32 v16, v82, v83
	v_cvt_pk_bf16_f32 v17, v78, v79
	global_store_dwordx2 v[44:45], v[16:17], off offset:512
	global_load_dwordx4 v[38:41], v[28:29], off offset:48
	s_nop 0
	global_load_dwordx4 v[42:45], v[28:29], off offset:32
	global_load_dwordx4 v[46:49], v[28:29], off offset:16
	global_load_dwordx4 v[50:53], v[28:29], off
	global_load_dwordx4 v[54:57], v[60:61], off offset:48
	global_load_dwordx4 v[98:101], v[60:61], off offset:16
	global_load_dwordx4 v[84:87], v[60:61], off offset:32
	global_load_dwordx4 v[102:105], v[60:61], off
	global_load_dwordx4 v[106:109], v[62:63], off offset:48
	global_load_dwordx4 v[110:113], v[62:63], off offset:16
	global_load_dwordx4 v[114:117], v[62:63], off offset:32
	global_load_dwordx4 v[118:121], v[62:63], off
	global_load_dwordx4 v[122:125], v[64:65], off offset:48
	global_load_dwordx4 v[126:129], v[64:65], off offset:16
	global_load_dwordx4 v[130:133], v[64:65], off offset:32
	global_load_dwordx4 v[134:137], v[64:65], off
	global_load_dwordx4 v[144:147], v[66:67], off offset:48
	v_mov_b64_e32 v[148:149], v[192:193]
	v_mov_b64_e32 v[150:151], v[194:195]
	v_mov_b64_e32 v[152:153], v[196:197]
	v_mov_b64_e32 v[154:155], v[198:199]
	v_mov_b64_e32 v[156:157], v[200:201]
	v_mov_b64_e32 v[158:159], v[202:203]
	v_mov_b64_e32 v[16:17], v[204:205]
	v_mov_b64_e32 v[18:19], v[206:207]
	v_mov_b64_e32 v[32:33], v[208:209]
	v_mov_b64_e32 v[34:35], v[210:211]
	v_mov_b64_e32 v[184:185], v[212:213]
	v_mov_b64_e32 v[186:187], v[214:215]
	v_mov_b64_e32 v[188:189], v[216:217]
	v_mov_b64_e32 v[190:191], v[218:219]
	s_waitcnt vmcnt(13)
	v_pk_fma_f32 v[50:51], v[50:51], v[22:23], 0 op_sel_hi:[1,0,0]
	s_nop 0
	v_pk_fma_f32 v[42:43], v[42:43], v[22:23], v[50:51] op_sel:[0,1,0]
	s_waitcnt vmcnt(9)
	v_pk_fma_f32 v[42:43], v[102:103], v[20:21], v[42:43] op_sel_hi:[1,0,1]
	s_nop 0
	v_pk_fma_f32 v[42:43], v[84:85], v[20:21], v[42:43] op_sel:[0,1,0]
	s_waitcnt vmcnt(5)
	v_pk_fma_f32 v[42:43], v[26:27], v[118:119], v[42:43] op_sel_hi:[0,1,1]
	v_pk_fma_f32 v[42:43], v[26:27], v[114:115], v[42:43] op_sel:[1,0,0]
	s_waitcnt vmcnt(1)
	v_pk_fma_f32 v[42:43], v[24:25], v[134:135], v[42:43] op_sel_hi:[0,1,1]
	v_pk_fma_f32 v[42:43], v[24:25], v[130:131], v[42:43] op_sel:[1,0,0]
	s_waitcnt vmcnt(0)
	v_pk_fma_f32 v[42:43], v[36:37], v[156:157], v[42:43] op_sel_hi:[0,1,1]
	v_pk_fma_f32 v[42:43], v[36:37], v[152:153], v[42:43] op_sel:[1,0,0]
	s_waitcnt vmcnt(0)
; __device__ __forceinline__ void phase_norm(const Ctx& c, const float* xin_p, const float* xin_s, float* X, int grow0, int nrows, const float* gamma, bf16_t* dst, const float* wif, float* gif) {
;     ...
; #pragma unroll
;             for (int i = 0; i < 4; ++i)
; #pragma unroll
;                 for (int e = 0; e < 4; ++e) {
;                     const float* wp = wif + (size_t)(256 * i + 4 * lane + e) * 8; const f32x4 w0 = *(const f32x4*)wp, w1 = *(const f32x4*)(wp + 4);
;                     a8[0] += v[i][e] * w0[0]; a8[1] += v[i][e] * w0[1]; a8[2] += v[i][e] * w0[2]; a8[3] += v[i][e] * w0[3];
;                     a8[4] += v[i][e] * w1[0]; a8[5] += v[i][e] * w1[1]; a8[6] += v[i][e] * w1[2]; a8[7] += v[i][e] * w1[3];
;                 }
	v_pk_fma_f32 v[90:91], v[80:81], v[188:189], v[42:43] op_sel_hi:[0,1,1]
	v_pk_fma_f32 v[42:43], v[52:53], v[22:23], 0 op_sel_hi:[1,0,0]
	v_pk_fma_f32 v[32:33], v[80:81], v[32:33], v[90:91] op_sel:[1,0,0]
	v_pk_fma_f32 v[42:43], v[44:45], v[22:23], v[42:43] op_sel:[0,1,0]
	s_nop 0
	v_pk_fma_f32 v[42:43], v[104:105], v[20:21], v[42:43] op_sel_hi:[1,0,1]
	s_nop 0
	v_pk_fma_f32 v[42:43], v[86:87], v[20:21], v[42:43] op_sel:[0,1,0]
	s_nop 0
	v_pk_fma_f32 v[42:43], v[26:27], v[120:121], v[42:43] op_sel_hi:[0,1,1]
	v_pk_fma_f32 v[42:43], v[26:27], v[116:117], v[42:43] op_sel:[1,0,0]
	s_nop 0
	v_pk_fma_f32 v[42:43], v[24:25], v[136:137], v[42:43] op_sel_hi:[0,1,1]
	v_pk_fma_f32 v[42:43], v[24:25], v[132:133], v[42:43] op_sel:[1,0,0]
	s_nop 0
	v_pk_fma_f32 v[42:43], v[36:37], v[158:159], v[42:43] op_sel_hi:[0,1,1]
	v_pk_fma_f32 v[42:43], v[36:37], v[154:155], v[42:43] op_sel:[1,0,0]
	s_nop 0
	v_pk_fma_f32 v[88:89], v[80:81], v[190:191], v[42:43] op_sel_hi:[0,1,1]
	v_pk_fma_f32 v[42:43], v[46:47], v[22:23], 0 op_sel_hi:[1,0,0]
	v_pk_fma_f32 v[34:35], v[80:81], v[34:35], v[88:89] op_sel:[1,0,0]
	v_pk_fma_f32 v[38:39], v[38:39], v[22:23], v[42:43] op_sel:[0,1,0]
	s_nop 0
	v_pk_fma_f32 v[38:39], v[98:99], v[20:21], v[38:39] op_sel_hi:[1,0,1]
	s_nop 0
	v_pk_fma_f32 v[38:39], v[54:55], v[20:21], v[38:39] op_sel:[0,1,0]
	s_nop 0
	v_pk_fma_f32 v[38:39], v[26:27], v[110:111], v[38:39] op_sel_hi:[0,1,1]
	v_pk_fma_f32 v[38:39], v[26:27], v[106:107], v[38:39] op_sel:[1,0,0]
	s_nop 0
	v_pk_fma_f32 v[38:39], v[24:25], v[126:127], v[38:39] op_sel_hi:[0,1,1]
	v_pk_fma_f32 v[38:39], v[24:25], v[122:123], v[38:39] op_sel:[1,0,0]
	s_nop 0
	v_pk_fma_f32 v[38:39], v[36:37], v[148:149], v[38:39] op_sel_hi:[0,1,1]
	v_pk_fma_f32 v[38:39], v[36:37], v[144:145], v[38:39] op_sel:[1,0,0]
	s_nop 0
	v_pk_fma_f32 v[86:87], v[80:81], v[184:185], v[38:39] op_sel_hi:[0,1,1]
	v_pk_fma_f32 v[38:39], v[48:49], v[22:23], 0 op_sel_hi:[1,0,0]
	v_pk_fma_f32 v[16:17], v[80:81], v[16:17], v[86:87] op_sel:[1,0,0]
	v_pk_fma_f32 v[22:23], v[40:41], v[22:23], v[38:39] op_sel:[0,1,0]
	s_nop 0
	v_pk_fma_f32 v[22:23], v[100:101], v[20:21], v[22:23] op_sel_hi:[1,0,1]
	s_nop 0
	v_pk_fma_f32 v[20:21], v[56:57], v[20:21], v[22:23] op_sel:[0,1,0]
	s_nop 0
	v_pk_fma_f32 v[20:21], v[26:27], v[112:113], v[20:21] op_sel_hi:[0,1,1]
	v_pk_fma_f32 v[20:21], v[26:27], v[108:109], v[20:21] op_sel:[1,0,0]
	s_nop 0
	v_pk_fma_f32 v[20:21], v[24:25], v[128:129], v[20:21] op_sel_hi:[0,1,1]
	v_pk_fma_f32 v[20:21], v[24:25], v[124:125], v[20:21] op_sel:[1,0,0]
	s_nop 0
	v_pk_fma_f32 v[20:21], v[36:37], v[150:151], v[20:21] op_sel_hi:[0,1,1]
	v_pk_fma_f32 v[20:21], v[36:37], v[146:147], v[20:21] op_sel:[1,0,0]
	s_nop 0
	v_pk_fma_f32 v[84:85], v[80:81], v[186:187], v[20:21] op_sel_hi:[0,1,1]
	v_mov_b64_e32 v[20:21], v[220:221]
	v_mov_b64_e32 v[22:23], v[222:223]
	v_mov_b64_e32 v[24:25], v[224:225]
	v_mov_b64_e32 v[26:27], v[226:227]
	v_mov_b64_e32 v[44:45], v[228:229]
	v_mov_b64_e32 v[46:47], v[230:231]
	v_mov_b64_e32 v[48:49], v[232:233]
	v_mov_b64_e32 v[50:51], v[234:235]
	v_mov_b64_e32 v[36:37], v[236:237]
	v_mov_b64_e32 v[38:39], v[238:239]
	v_mov_b64_e32 v[40:41], v[240:241]
	v_mov_b64_e32 v[42:43], v[242:243]
	v_mov_b64_e32 v[52:53], v[244:245]
	v_mov_b64_e32 v[54:55], v[246:247]
	v_mov_b64_e32 v[56:57], v[248:249]
	v_mov_b64_e32 v[58:59], v[250:251]
	v_pk_fma_f32 v[18:19], v[80:81], v[18:19], v[84:85] op_sel:[1,0,0]
	s_waitcnt vmcnt(6)
	v_pk_fma_f32 v[16:17], v[82:83], v[24:25], v[16:17] op_sel_hi:[0,1,1]
	v_pk_fma_f32 v[18:19], v[82:83], v[26:27], v[18:19] op_sel_hi:[0,1,1]
	s_waitcnt vmcnt(4)
	v_pk_fma_f32 v[32:33], v[82:83], v[48:49], v[32:33] op_sel_hi:[0,1,1]
	v_pk_fma_f32 v[34:35], v[82:83], v[50:51], v[34:35] op_sel_hi:[0,1,1]
	v_pk_fma_f32 v[32:33], v[82:83], v[44:45], v[32:33] op_sel:[1,0,0]
	v_pk_fma_f32 v[34:35], v[82:83], v[46:47], v[34:35] op_sel:[1,0,0]
	v_pk_fma_f32 v[16:17], v[82:83], v[20:21], v[16:17] op_sel:[1,0,0]
	v_pk_fma_f32 v[18:19], v[82:83], v[22:23], v[18:19] op_sel:[1,0,0]
	s_waitcnt vmcnt(0)
; __device__ __forceinline__ void phase_norm(const Ctx& c, const float* xin_p, const float* xin_s, float* X, int grow0, int nrows, const float* gamma, bf16_t* dst, const float* wif, float* gif) {
;     ...
; #pragma unroll
;             for (int i = 0; i < 4; ++i)
; #pragma unroll
;                 for (int e = 0; e < 4; ++e) {
;                     const float* wp = wif + (size_t)(256 * i + 4 * lane + e) * 8; const f32x4 w0 = *(const f32x4*)wp, w1 = *(const f32x4*)(wp + 4);
;                     a8[0] += v[i][e] * w0[0]; a8[1] += v[i][e] * w0[1]; a8[2] += v[i][e] * w0[2]; a8[3] += v[i][e] * w0[3];
;                     a8[4] += v[i][e] * w1[0]; a8[5] += v[i][e] * w1[1]; a8[6] += v[i][e] * w1[2]; a8[7] += v[i][e] * w1[3];
;                 }
; #pragma unroll
;             for (int j = 0; j < 8; ++j) a8[j] = wsum(a8[j]);
;             if (lane == 0) {
; #pragma unroll
;                 for (int j = 0; j < 8; ++j) gif[(size_t)r * 8 + j] = a8[j];
;             }
;         }
	v_pk_fma_f32 v[32:33], v[78:79], v[56:57], v[32:33] op_sel_hi:[0,1,1]
	v_pk_fma_f32 v[34:35], v[78:79], v[58:59], v[34:35] op_sel_hi:[0,1,1]
	v_pk_fma_f32 v[16:17], v[78:79], v[40:41], v[16:17] op_sel_hi:[0,1,1]
	v_pk_fma_f32 v[18:19], v[78:79], v[42:43], v[18:19] op_sel_hi:[0,1,1]
	v_pk_fma_f32 v[32:33], v[78:79], v[52:53], v[32:33] op_sel:[1,0,0]
	v_pk_fma_f32 v[34:35], v[78:79], v[54:55], v[34:35] op_sel:[1,0,0]
	v_pk_fma_f32 v[16:17], v[78:79], v[36:37], v[16:17] op_sel:[1,0,0]
	v_pk_fma_f32 v[18:19], v[78:79], v[38:39], v[18:19] op_sel:[1,0,0]
	ds_bpermute_b32 v44, v30, v32
	ds_bpermute_b32 v45, v30, v33
	ds_bpermute_b32 v46, v30, v34
	ds_bpermute_b32 v47, v30, v35
	ds_bpermute_b32 v20, v30, v16
	ds_bpermute_b32 v21, v30, v17
	ds_bpermute_b32 v22, v30, v18
	ds_bpermute_b32 v23, v30, v19
	s_waitcnt lgkmcnt(6)
	v_pk_add_f32 v[32:33], v[32:33], v[44:45]
	s_waitcnt lgkmcnt(4)
	v_pk_add_f32 v[34:35], v[34:35], v[46:47]
	s_waitcnt lgkmcnt(2)
	v_pk_add_f32 v[16:17], v[16:17], v[20:21]
	ds_bpermute_b32 v44, v92, v32
	s_waitcnt lgkmcnt(1)
	v_pk_add_f32 v[18:19], v[18:19], v[22:23]
	ds_bpermute_b32 v45, v92, v33
	ds_bpermute_b32 v46, v92, v34
	ds_bpermute_b32 v47, v92, v35
	ds_bpermute_b32 v20, v92, v16
	ds_bpermute_b32 v21, v92, v17
	ds_bpermute_b32 v22, v92, v18
	ds_bpermute_b32 v23, v92, v19
	s_waitcnt lgkmcnt(6)
	v_pk_add_f32 v[32:33], v[32:33], v[44:45]
	s_waitcnt lgkmcnt(4)
	v_pk_add_f32 v[34:35], v[34:35], v[46:47]
	s_waitcnt lgkmcnt(2)
	v_pk_add_f32 v[16:17], v[16:17], v[20:21]
	ds_bpermute_b32 v44, v93, v32
	s_waitcnt lgkmcnt(1)
	v_pk_add_f32 v[18:19], v[18:19], v[22:23]
	ds_bpermute_b32 v45, v93, v33
	ds_bpermute_b32 v46, v93, v34
	ds_bpermute_b32 v47, v93, v35
	ds_bpermute_b32 v20, v93, v16
	ds_bpermute_b32 v21, v93, v17
	ds_bpermute_b32 v22, v93, v18
	ds_bpermute_b32 v23, v93, v19
	s_waitcnt lgkmcnt(6)
	v_pk_add_f32 v[32:33], v[32:33], v[44:45]
	s_waitcnt lgkmcnt(4)
	v_pk_add_f32 v[34:35], v[34:35], v[46:47]
	s_waitcnt lgkmcnt(2)
	v_pk_add_f32 v[16:17], v[16:17], v[20:21]
	ds_bpermute_b32 v44, v94, v32
	s_waitcnt lgkmcnt(1)
	v_pk_add_f32 v[18:19], v[18:19], v[22:23]
	ds_bpermute_b32 v45, v94, v33
	ds_bpermute_b32 v46, v94, v34
	ds_bpermute_b32 v47, v94, v35
	ds_bpermute_b32 v20, v94, v16
	ds_bpermute_b32 v21, v94, v17
	ds_bpermute_b32 v22, v94, v18
	ds_bpermute_b32 v23, v94, v19
	s_waitcnt lgkmcnt(6)
	v_pk_add_f32 v[32:33], v[32:33], v[44:45]
	s_waitcnt lgkmcnt(4)
	v_pk_add_f32 v[34:35], v[34:35], v[46:47]
	s_waitcnt lgkmcnt(2)
	v_pk_add_f32 v[16:17], v[16:17], v[20:21]
	ds_bpermute_b32 v44, v95, v32
	s_waitcnt lgkmcnt(1)
	v_pk_add_f32 v[18:19], v[18:19], v[22:23]
	ds_bpermute_b32 v45, v95, v33
	ds_bpermute_b32 v46, v95, v34
	ds_bpermute_b32 v47, v95, v35
	ds_bpermute_b32 v20, v95, v16
	ds_bpermute_b32 v21, v95, v17
	ds_bpermute_b32 v22, v95, v18
	ds_bpermute_b32 v23, v95, v19
	s_waitcnt lgkmcnt(6)
	v_pk_add_f32 v[32:33], v[32:33], v[44:45]
	s_waitcnt lgkmcnt(4)
	v_pk_add_f32 v[34:35], v[34:35], v[46:47]
	s_waitcnt lgkmcnt(2)
	v_pk_add_f32 v[16:17], v[16:17], v[20:21]
	ds_bpermute_b32 v44, v96, v32
	s_waitcnt lgkmcnt(1)
	v_pk_add_f32 v[18:19], v[18:19], v[22:23]
	ds_bpermute_b32 v45, v96, v33
	ds_bpermute_b32 v46, v96, v34
	ds_bpermute_b32 v47, v96, v35
	ds_bpermute_b32 v20, v96, v16
	ds_bpermute_b32 v21, v96, v17
	ds_bpermute_b32 v22, v96, v18
	ds_bpermute_b32 v23, v96, v19
	s_and_saveexec_b64 s[14:15], vcc
	s_cbranch_execz .LBB0_410
	s_add_u32 s16, s82, s4
	s_addc_u32 s17, s83, s5
	s_waitcnt lgkmcnt(6)
	v_pk_add_f32 v[24:25], v[32:33], v[44:45]
	s_waitcnt lgkmcnt(4)
	v_pk_add_f32 v[26:27], v[34:35], v[46:47]
	s_waitcnt lgkmcnt(2)
	v_pk_add_f32 v[16:17], v[16:17], v[20:21]
	s_waitcnt lgkmcnt(0)
	v_pk_add_f32 v[18:19], v[18:19], v[22:23]
	global_store_dwordx4 v165, v[24:27], s[16:17]
	global_store_dwordx4 v165, v[16:19], s[16:17] offset:16
	s_branch .LBB0_410
